# plus mix_pass_c head loop, p0 X/XB row loop and final-norm row loop: row loads batched up front with counted vmcnt (were serialized one round trip each)
# speedup vs baseline: 1.0409x; 1.0144x over previous
.LBB0_250:
	global_load_dwordx4 v[12:15], v0, s[20:21]
	global_load_dwordx4 v[16:19], v0, s[20:21] offset:1024
	global_load_dwordx4 v[20:23], v0, s[20:21] offset:2048
	global_load_dwordx4 v[24:27], v0, s[20:21] offset:3072
	global_load_dwordx4 v[28:31], v6, s[20:21]
	global_load_dwordx4 v[32:35], v7, s[20:21]
	global_load_dwordx4 v[36:39], v8, s[20:21]
	global_load_dwordx4 v[40:43], v9, s[20:21]
	s_lshl_b64 s[16:17], s[14:15], 13
	s_add_u32 s16, s2, s16
	s_addc_u32 s17, s3, s17
	s_lshl_b64 s[24:25], s[14:15], 12
	v_lshl_add_u64 v[4:5], v[2:3], 0, s[24:25]
	s_waitcnt vmcnt(7)
	v_and_b32_sdwa v45, v15, v10 dst_sel:DWORD dst_unused:UNUSED_PAD src0_sel:WORD_1 src1_sel:DWORD
	v_and_b32_sdwa v46, v13, v10 dst_sel:DWORD dst_unused:UNUSED_PAD src0_sel:WORD_1 src1_sel:DWORD
	v_and_b32_sdwa v11, v14, v10 dst_sel:DWORD dst_unused:UNUSED_PAD src0_sel:WORD_1 src1_sel:DWORD
	v_and_b32_sdwa v44, v12, v10 dst_sel:DWORD dst_unused:UNUSED_PAD src0_sel:WORD_1 src1_sel:DWORD
	v_add3_u32 v45, v15, v45, s19
	v_add3_u32 v46, v13, v46, s19
	v_add3_u32 v44, v12, v44, s19
	v_add3_u32 v11, v14, v11, s19
	v_and_b32_e32 v45, 0xffff0000, v45
	v_and_b32_e32 v46, 0xffff0000, v46
	v_or_b32_sdwa v45, v45, v11 dst_sel:DWORD dst_unused:UNUSED_PAD src0_sel:DWORD src1_sel:WORD_1
	v_or_b32_sdwa v44, v46, v44 dst_sel:DWORD dst_unused:UNUSED_PAD src0_sel:DWORD src1_sel:WORD_1
	global_store_dwordx4 v0, v[12:15], s[16:17]
	global_store_dwordx2 v[4:5], v[44:45], off
	s_waitcnt vmcnt(8)
	v_and_b32_sdwa v45, v19, v10 dst_sel:DWORD dst_unused:UNUSED_PAD src0_sel:WORD_1 src1_sel:DWORD
	v_and_b32_sdwa v46, v17, v10 dst_sel:DWORD dst_unused:UNUSED_PAD src0_sel:WORD_1 src1_sel:DWORD
	v_and_b32_sdwa v11, v18, v10 dst_sel:DWORD dst_unused:UNUSED_PAD src0_sel:WORD_1 src1_sel:DWORD
	v_and_b32_sdwa v44, v16, v10 dst_sel:DWORD dst_unused:UNUSED_PAD src0_sel:WORD_1 src1_sel:DWORD
	v_add3_u32 v45, v19, v45, s19
	v_add3_u32 v46, v17, v46, s19
	v_add3_u32 v44, v16, v44, s19
	v_add3_u32 v11, v18, v11, s19
	v_and_b32_e32 v45, 0xffff0000, v45
	v_and_b32_e32 v46, 0xffff0000, v46
	v_or_b32_sdwa v45, v45, v11 dst_sel:DWORD dst_unused:UNUSED_PAD src0_sel:DWORD src1_sel:WORD_1
	v_or_b32_sdwa v44, v46, v44 dst_sel:DWORD dst_unused:UNUSED_PAD src0_sel:DWORD src1_sel:WORD_1
	global_store_dwordx4 v0, v[16:19], s[16:17] offset:1024
	global_store_dwordx2 v[4:5], v[44:45], off offset:512
	s_waitcnt vmcnt(9)
	v_and_b32_sdwa v45, v23, v10 dst_sel:DWORD dst_unused:UNUSED_PAD src0_sel:WORD_1 src1_sel:DWORD
	v_and_b32_sdwa v46, v21, v10 dst_sel:DWORD dst_unused:UNUSED_PAD src0_sel:WORD_1 src1_sel:DWORD
	v_and_b32_sdwa v11, v22, v10 dst_sel:DWORD dst_unused:UNUSED_PAD src0_sel:WORD_1 src1_sel:DWORD
	v_and_b32_sdwa v44, v20, v10 dst_sel:DWORD dst_unused:UNUSED_PAD src0_sel:WORD_1 src1_sel:DWORD
	v_add3_u32 v45, v23, v45, s19
	v_add3_u32 v46, v21, v46, s19
	v_add3_u32 v44, v20, v44, s19
	v_add3_u32 v11, v22, v11, s19
	v_and_b32_e32 v45, 0xffff0000, v45
	v_and_b32_e32 v46, 0xffff0000, v46
	v_or_b32_sdwa v45, v45, v11 dst_sel:DWORD dst_unused:UNUSED_PAD src0_sel:DWORD src1_sel:WORD_1
	v_or_b32_sdwa v44, v46, v44 dst_sel:DWORD dst_unused:UNUSED_PAD src0_sel:DWORD src1_sel:WORD_1
	global_store_dwordx4 v0, v[20:23], s[16:17] offset:2048
	global_store_dwordx2 v[4:5], v[44:45], off offset:1024
	s_waitcnt vmcnt(10)
	v_and_b32_sdwa v45, v27, v10 dst_sel:DWORD dst_unused:UNUSED_PAD src0_sel:WORD_1 src1_sel:DWORD
	v_and_b32_sdwa v46, v25, v10 dst_sel:DWORD dst_unused:UNUSED_PAD src0_sel:WORD_1 src1_sel:DWORD
	v_and_b32_sdwa v11, v26, v10 dst_sel:DWORD dst_unused:UNUSED_PAD src0_sel:WORD_1 src1_sel:DWORD
	v_and_b32_sdwa v44, v24, v10 dst_sel:DWORD dst_unused:UNUSED_PAD src0_sel:WORD_1 src1_sel:DWORD
	v_add3_u32 v45, v27, v45, s19
	v_add3_u32 v46, v25, v46, s19
	v_add3_u32 v44, v24, v44, s19
	v_add3_u32 v11, v26, v11, s19
	v_and_b32_e32 v45, 0xffff0000, v45
	v_and_b32_e32 v46, 0xffff0000, v46
	v_or_b32_sdwa v45, v45, v11 dst_sel:DWORD dst_unused:UNUSED_PAD src0_sel:DWORD src1_sel:WORD_1
	v_or_b32_sdwa v44, v46, v44 dst_sel:DWORD dst_unused:UNUSED_PAD src0_sel:DWORD src1_sel:WORD_1
	global_store_dwordx4 v0, v[24:27], s[16:17] offset:3072
	global_store_dwordx2 v[4:5], v[44:45], off offset:1536
	s_waitcnt vmcnt(11)
	v_and_b32_sdwa v45, v31, v10 dst_sel:DWORD dst_unused:UNUSED_PAD src0_sel:WORD_1 src1_sel:DWORD
	v_and_b32_sdwa v46, v29, v10 dst_sel:DWORD dst_unused:UNUSED_PAD src0_sel:WORD_1 src1_sel:DWORD
	v_and_b32_sdwa v11, v30, v10 dst_sel:DWORD dst_unused:UNUSED_PAD src0_sel:WORD_1 src1_sel:DWORD
	v_and_b32_sdwa v44, v28, v10 dst_sel:DWORD dst_unused:UNUSED_PAD src0_sel:WORD_1 src1_sel:DWORD
	v_add3_u32 v45, v31, v45, s19
	v_add3_u32 v46, v29, v46, s19
	v_add3_u32 v44, v28, v44, s19
	v_add3_u32 v11, v30, v11, s19
	v_and_b32_e32 v45, 0xffff0000, v45
	v_and_b32_e32 v46, 0xffff0000, v46
	v_or_b32_sdwa v45, v45, v11 dst_sel:DWORD dst_unused:UNUSED_PAD src0_sel:DWORD src1_sel:WORD_1
	v_or_b32_sdwa v44, v46, v44 dst_sel:DWORD dst_unused:UNUSED_PAD src0_sel:DWORD src1_sel:WORD_1
	global_store_dwordx4 v6, v[28:31], s[16:17]
	global_store_dwordx2 v[4:5], v[44:45], off offset:2048
	s_waitcnt vmcnt(12)
	v_and_b32_sdwa v45, v35, v10 dst_sel:DWORD dst_unused:UNUSED_PAD src0_sel:WORD_1 src1_sel:DWORD
	v_and_b32_sdwa v46, v33, v10 dst_sel:DWORD dst_unused:UNUSED_PAD src0_sel:WORD_1 src1_sel:DWORD
	v_and_b32_sdwa v11, v34, v10 dst_sel:DWORD dst_unused:UNUSED_PAD src0_sel:WORD_1 src1_sel:DWORD
	v_and_b32_sdwa v44, v32, v10 dst_sel:DWORD dst_unused:UNUSED_PAD src0_sel:WORD_1 src1_sel:DWORD
	v_add3_u32 v45, v35, v45, s19
	v_add3_u32 v46, v33, v46, s19
	v_add3_u32 v44, v32, v44, s19
	v_add3_u32 v11, v34, v11, s19
	v_and_b32_e32 v45, 0xffff0000, v45
	v_and_b32_e32 v46, 0xffff0000, v46
	v_or_b32_sdwa v45, v45, v11 dst_sel:DWORD dst_unused:UNUSED_PAD src0_sel:DWORD src1_sel:WORD_1
	v_or_b32_sdwa v44, v46, v44 dst_sel:DWORD dst_unused:UNUSED_PAD src0_sel:DWORD src1_sel:WORD_1
	global_store_dwordx4 v7, v[32:35], s[16:17]
	global_store_dwordx2 v[4:5], v[44:45], off offset:2560
	s_waitcnt vmcnt(13)
	v_and_b32_sdwa v45, v39, v10 dst_sel:DWORD dst_unused:UNUSED_PAD src0_sel:WORD_1 src1_sel:DWORD
	v_and_b32_sdwa v46, v37, v10 dst_sel:DWORD dst_unused:UNUSED_PAD src0_sel:WORD_1 src1_sel:DWORD
	v_and_b32_sdwa v11, v38, v10 dst_sel:DWORD dst_unused:UNUSED_PAD src0_sel:WORD_1 src1_sel:DWORD
	v_and_b32_sdwa v44, v36, v10 dst_sel:DWORD dst_unused:UNUSED_PAD src0_sel:WORD_1 src1_sel:DWORD
	v_add3_u32 v45, v39, v45, s19
	v_add3_u32 v46, v37, v46, s19
	v_add3_u32 v44, v36, v44, s19
	v_add3_u32 v11, v38, v11, s19
	v_and_b32_e32 v45, 0xffff0000, v45
	v_and_b32_e32 v46, 0xffff0000, v46
	v_or_b32_sdwa v45, v45, v11 dst_sel:DWORD dst_unused:UNUSED_PAD src0_sel:DWORD src1_sel:WORD_1
	v_or_b32_sdwa v44, v46, v44 dst_sel:DWORD dst_unused:UNUSED_PAD src0_sel:DWORD src1_sel:WORD_1
	global_store_dwordx4 v8, v[36:39], s[16:17]
	global_store_dwordx2 v[4:5], v[44:45], off offset:3072
	v_mul_f32_e32 v11, v13, v13
	v_mul_f32_e32 v13, v15, v15
	v_fmac_f32_e32 v11, v12, v12
	v_fmac_f32_e32 v13, v14, v14
	v_add_f32_e32 v11, v11, v13
	v_mul_f32_e32 v12, v17, v17
	v_mul_f32_e32 v13, v19, v19
	v_fmac_f32_e32 v12, v16, v16
	v_fmac_f32_e32 v13, v18, v18
	v_add_f32_e32 v12, v12, v13
	v_add_f32_e32 v11, v11, v12
	v_mul_f32_e32 v12, v21, v21
	v_mul_f32_e32 v13, v23, v23
	v_fmac_f32_e32 v12, v20, v20
	v_fmac_f32_e32 v13, v22, v22
	v_add_f32_e32 v12, v12, v13
	v_add_f32_e32 v11, v11, v12
	v_mul_f32_e32 v12, v25, v25
	v_mul_f32_e32 v13, v27, v27
	v_fmac_f32_e32 v12, v24, v24
	v_fmac_f32_e32 v13, v26, v26
	v_add_f32_e32 v12, v12, v13
	v_add_f32_e32 v11, v11, v12
	v_mul_f32_e32 v12, v29, v29
	v_mul_f32_e32 v13, v31, v31
	v_fmac_f32_e32 v12, v28, v28
	v_fmac_f32_e32 v13, v30, v30
	v_add_f32_e32 v12, v12, v13
	v_add_f32_e32 v11, v11, v12
	v_mul_f32_e32 v12, v33, v33
	v_mul_f32_e32 v13, v35, v35
	v_fmac_f32_e32 v12, v32, v32
	v_fmac_f32_e32 v13, v34, v34
	v_add_f32_e32 v12, v12, v13
	v_add_f32_e32 v11, v11, v12
	v_mul_f32_e32 v12, v37, v37
	v_mul_f32_e32 v13, v39, v39
	v_fmac_f32_e32 v12, v36, v36
	v_fmac_f32_e32 v13, v38, v38
	v_add_f32_e32 v12, v12, v13
	v_add_f32_e32 v11, v11, v12
	s_waitcnt vmcnt(14)
	v_and_b32_sdwa v13, v40, v10 dst_sel:DWORD dst_unused:UNUSED_PAD src0_sel:WORD_1 src1_sel:DWORD
	v_and_b32_sdwa v14, v43, v10 dst_sel:DWORD dst_unused:UNUSED_PAD src0_sel:WORD_1 src1_sel:DWORD
	v_and_b32_sdwa v15, v41, v10 dst_sel:DWORD dst_unused:UNUSED_PAD src0_sel:WORD_1 src1_sel:DWORD
	v_mul_f32_e32 v16, v41, v41
	v_mul_f32_e32 v17, v43, v43
	v_and_b32_sdwa v12, v42, v10 dst_sel:DWORD dst_unused:UNUSED_PAD src0_sel:WORD_1 src1_sel:DWORD
	v_add3_u32 v18, v40, v13, s19
	v_add3_u32 v13, v43, v14, s19
	v_add3_u32 v14, v41, v15, s19
	v_fmac_f32_e32 v16, v40, v40
	v_fmac_f32_e32 v17, v42, v42
	v_add3_u32 v12, v42, v12, s19
	v_and_b32_e32 v13, 0xffff0000, v13
	v_and_b32_e32 v14, 0xffff0000, v14
	v_add_f32_e32 v15, v16, v17
	v_or_b32_sdwa v13, v13, v12 dst_sel:DWORD dst_unused:UNUSED_PAD src0_sel:DWORD src1_sel:WORD_1
	v_or_b32_sdwa v12, v14, v18 dst_sel:DWORD dst_unused:UNUSED_PAD src0_sel:DWORD src1_sel:WORD_1
	v_add_f32_e32 v11, v11, v15
	global_store_dwordx4 v9, v[40:43], s[16:17]
	global_store_dwordx2 v[4:5], v[12:13], off offset:3584
	v_add_f32_dpp v4, v11, v11 quad_perm:[1,0,3,2] row_mask:0xf bank_mask:0xf bound_ctrl:1
	s_nop 1
	v_add_f32_dpp v4, v4, v4 quad_perm:[2,3,0,1] row_mask:0xf bank_mask:0xf bound_ctrl:1
	s_nop 1
	v_add_f32_dpp v4, v4, v4 row_half_mirror row_mask:0xf bank_mask:0xf bound_ctrl:1
	s_nop 1
	v_add_f32_dpp v4, v4, v4 row_mirror row_mask:0xf bank_mask:0xf bound_ctrl:1
	s_nop 0
	v_readlane_b32 s20, v4, 0
	v_readlane_b32 s6, v4, 16
	v_readlane_b32 s21, v4, 32
	v_readlane_b32 s24, v4, 48
	s_and_saveexec_b64 s[16:17], s[4:5]
	s_cbranch_execz .LBB0_245
	s_lshl_b64 s[14:15], s[14:15], 2
	v_mov_b32_e32 v4, s6
	v_mov_b32_e32 v5, s24
	s_add_u32 s14, s22, s14
	v_pk_add_f32 v[4:5], s[20:21], v[4:5]
	s_addc_u32 s15, s23, s15
	v_add_f32_e32 v4, v4, v5
	global_store_dword v1, v4, s[14:15]
	s_branch .LBB0_245

.LBB0_1740:
	s_add_u32 s40, s14, 0x33400000
	s_addc_u32 s41, s15, 0
	s_add_u32 s42, s14, 0x412c2000
	s_addc_u32 s43, s15, 0
	v_lshl_add_u64 v[28:29], v[6:7], 0, s[40:41]
	v_lshl_add_u64 v[30:31], v[8:9], 0, s[14:15]
	v_lshl_add_u64 v[32:33], v[10:11], 0, s[14:15]
	v_lshl_add_u64 v[34:35], v[4:5], 0, s[42:43]
	s_and_b64 vcc, exec, s[10:11]
	s_cbranch_vccz .Lpc_smp
	s_add_i32 s6, s26, s27
	s_ashr_i32 s7, s6, 31
	s_lshl_b64 s[6:7], s[6:7], 11
	s_or_b32 s6, s6, s25
	s_mulk_i32 s7, 0x180
	s_mul_hi_u32 s18, s6, 0x180
	s_add_i32 s7, s18, s7
	s_mulk_i32 s6, 0x180
	v_lshl_add_u64 v[36:37], s[6:7], 2, v[2:3]
	s_add_i32 s6, s26, s27
	s_add_i32 s6, s6, 1
	s_ashr_i32 s7, s6, 31
	s_lshl_b64 s[6:7], s[6:7], 11
	s_or_b32 s6, s6, s25
	s_mulk_i32 s7, 0x180
	s_mul_hi_u32 s18, s6, 0x180
	s_add_i32 s7, s18, s7
	s_mulk_i32 s6, 0x180
	v_lshl_add_u64 v[38:39], s[6:7], 2, v[2:3]
	s_add_i32 s6, s26, s27
	s_add_i32 s6, s6, 2
	s_ashr_i32 s7, s6, 31
	s_lshl_b64 s[6:7], s[6:7], 11
	s_or_b32 s6, s6, s25
	s_mulk_i32 s7, 0x180
	s_mul_hi_u32 s18, s6, 0x180
	s_add_i32 s7, s18, s7
	s_mulk_i32 s6, 0x180
	v_lshl_add_u64 v[40:41], s[6:7], 2, v[2:3]
	s_add_i32 s6, s26, s27
	s_add_i32 s6, s6, 3
	s_ashr_i32 s7, s6, 31
	s_lshl_b64 s[6:7], s[6:7], 11
	s_or_b32 s6, s6, s25
	s_mulk_i32 s7, 0x180
	s_mul_hi_u32 s18, s6, 0x180
	s_add_i32 s7, s18, s7
	s_mulk_i32 s6, 0x180
	v_lshl_add_u64 v[42:43], s[6:7], 2, v[2:3]
	s_branch .Lpc_adr
.Lpc_smp:
	s_add_u32 s6, s12, 0xffffdc00
	s_addc_u32 s7, s13, -1
	v_lshl_add_u64 v[36:37], s[6:7], 2, v[2:3]
	s_add_u32 s6, s12, 0xffffe800
	s_addc_u32 s7, s13, -1
	v_lshl_add_u64 v[38:39], s[6:7], 2, v[2:3]
	s_add_u32 s6, s12, 0xfffff400
	s_addc_u32 s7, s13, -1
	v_lshl_add_u64 v[40:41], s[6:7], 2, v[2:3]
	v_lshl_add_u64 v[42:43], s[12:13], 2, v[2:3]
.Lpc_adr:
	global_load_dword v44, v[28:29], off
	global_load_dword v45, v[36:37], off
	global_load_dword v46, v[34:35], off
	global_load_dword v47, v[30:31], off
	global_load_dword v48, v[32:33], off
	global_load_dword v49, v1, s[16:17] offset:-8
	global_load_dword v50, v[28:29], off offset:256
	global_load_dword v51, v[38:39], off
	global_load_dword v52, v[34:35], off offset:256
	global_load_dword v53, v[30:31], off offset:256
	global_load_dword v54, v[32:33], off offset:256
	global_load_dword v55, v1, s[16:17] offset:-4
	global_load_dword v56, v[28:29], off offset:512
	global_load_dword v57, v[40:41], off
	global_load_dword v58, v[34:35], off offset:512
	global_load_dword v59, v[30:31], off offset:512
	global_load_dword v60, v[32:33], off offset:512
	global_load_dword v61, v1, s[16:17]
	global_load_dword v62, v[28:29], off offset:768
	global_load_dword v63, v[42:43], off
	global_load_dword v64, v[34:35], off offset:768
	global_load_dword v65, v[30:31], off offset:768
	global_load_dword v66, v[32:33], off offset:768
	global_load_dword v67, v1, s[16:17] offset:4
	s_waitcnt vmcnt(18)
	v_add_f32_dpp v16, v44, v44 quad_perm:[1,0,3,2] row_mask:0xf bank_mask:0xf bound_ctrl:1
	s_nop 1
	v_add_f32_dpp v16, v16, v16 quad_perm:[2,3,0,1] row_mask:0xf bank_mask:0xf bound_ctrl:1
	s_nop 1
	v_add_f32_dpp v16, v16, v16 row_half_mirror row_mask:0xf bank_mask:0xf bound_ctrl:1
	s_nop 1
	v_add_f32_dpp v16, v16, v16 row_mirror row_mask:0xf bank_mask:0xf bound_ctrl:1
	s_nop 0
	v_readlane_b32 s3, v16, 16
	v_readlane_b32 s5, v16, 48
	v_readlane_b32 s2, v16, 0
	v_readlane_b32 s4, v16, 32
	v_mov_b32_e32 v16, s3
	v_mov_b32_e32 v17, s5
	v_add_f32_e32 v16, s2, v16
	v_add_f32_e32 v17, s4, v17
	v_add_f32_e32 v16, v16, v17
	v_fmac_f32_e32 v44, 0xbc800000, v16
	v_mul_f32_e32 v16, v44, v44
	s_nop 1
	v_mov_b32_dpp v16, v16 quad_perm:[1,0,3,2] row_mask:0xf bank_mask:0xf bound_ctrl:1
	v_fmac_f32_e32 v16, v44, v44
	s_nop 1
	v_add_f32_dpp v16, v16, v16 quad_perm:[2,3,0,1] row_mask:0xf bank_mask:0xf bound_ctrl:1
	s_nop 1
	v_add_f32_dpp v16, v16, v16 row_half_mirror row_mask:0xf bank_mask:0xf bound_ctrl:1
	s_nop 1
	v_add_f32_dpp v16, v16, v16 row_mirror row_mask:0xf bank_mask:0xf bound_ctrl:1
	s_nop 0
	v_readlane_b32 s2, v16, 0
	v_readlane_b32 s4, v16, 16
	v_readlane_b32 s3, v16, 32
	v_readlane_b32 s5, v16, 48
	v_mov_b32_e32 v17, s4
	v_add_f32_e32 v17, s2, v17
	v_mov_b32_e32 v25, s5
	v_add_f32_e32 v25, s3, v25
	v_add_f32_e32 v17, v17, v25
	v_fmamk_f32 v17, v17, 0x3c800000, v210
	v_rsq_f32_e32 v17, v17
	s_nop 0
	v_mul_f32_e32 v44, v44, v17
	v_fmac_f32_e32 v47, v48, v44
	v_fmac_f32_e32 v47, v45, v49
	v_mul_f32_e32 v0, v46, v47
	v_bfe_u32 v24, v0, 16, 1
	v_add3_u32 v0, v0, v24, s85
	global_store_short_d16_hi v[14:15], v0, off offset:-256
	s_waitcnt vmcnt(13)
	v_add_f32_dpp v16, v50, v50 quad_perm:[1,0,3,2] row_mask:0xf bank_mask:0xf bound_ctrl:1
	s_nop 1
	v_add_f32_dpp v16, v16, v16 quad_perm:[2,3,0,1] row_mask:0xf bank_mask:0xf bound_ctrl:1
	s_nop 1
	v_add_f32_dpp v16, v16, v16 row_half_mirror row_mask:0xf bank_mask:0xf bound_ctrl:1
	s_nop 1
	v_add_f32_dpp v16, v16, v16 row_mirror row_mask:0xf bank_mask:0xf bound_ctrl:1
	s_nop 0
	v_readlane_b32 s3, v16, 16
	v_readlane_b32 s5, v16, 48
	v_readlane_b32 s2, v16, 0
	v_readlane_b32 s4, v16, 32
	v_mov_b32_e32 v16, s3
	v_mov_b32_e32 v17, s5
	v_add_f32_e32 v16, s2, v16
	v_add_f32_e32 v17, s4, v17
	v_add_f32_e32 v16, v16, v17
	v_fmac_f32_e32 v50, 0xbc800000, v16
	v_mul_f32_e32 v16, v50, v50
	s_nop 1
	v_mov_b32_dpp v16, v16 quad_perm:[1,0,3,2] row_mask:0xf bank_mask:0xf bound_ctrl:1
	v_fmac_f32_e32 v16, v50, v50
	s_nop 1
	v_add_f32_dpp v16, v16, v16 quad_perm:[2,3,0,1] row_mask:0xf bank_mask:0xf bound_ctrl:1
	s_nop 1
	v_add_f32_dpp v16, v16, v16 row_half_mirror row_mask:0xf bank_mask:0xf bound_ctrl:1
	s_nop 1
	v_add_f32_dpp v16, v16, v16 row_mirror row_mask:0xf bank_mask:0xf bound_ctrl:1
	s_nop 0
	v_readlane_b32 s2, v16, 0
	v_readlane_b32 s4, v16, 16
	v_readlane_b32 s3, v16, 32
	v_readlane_b32 s5, v16, 48
	v_mov_b32_e32 v17, s4
	v_add_f32_e32 v17, s2, v17
	v_mov_b32_e32 v25, s5
	v_add_f32_e32 v25, s3, v25
	v_add_f32_e32 v17, v17, v25
	v_fmamk_f32 v17, v17, 0x3c800000, v210
	v_rsq_f32_e32 v17, v17
	s_nop 0
	v_mul_f32_e32 v50, v50, v17
	v_fmac_f32_e32 v53, v54, v50
	v_fmac_f32_e32 v53, v51, v55
	v_mul_f32_e32 v0, v52, v53
	v_bfe_u32 v24, v0, 16, 1
	v_add3_u32 v0, v0, v24, s85
	global_store_short_d16_hi v[14:15], v0, off offset:-128
	s_waitcnt vmcnt(8)
	v_add_f32_dpp v16, v56, v56 quad_perm:[1,0,3,2] row_mask:0xf bank_mask:0xf bound_ctrl:1
	s_nop 1
	v_add_f32_dpp v16, v16, v16 quad_perm:[2,3,0,1] row_mask:0xf bank_mask:0xf bound_ctrl:1
	s_nop 1
	v_add_f32_dpp v16, v16, v16 row_half_mirror row_mask:0xf bank_mask:0xf bound_ctrl:1
	s_nop 1
	v_add_f32_dpp v16, v16, v16 row_mirror row_mask:0xf bank_mask:0xf bound_ctrl:1
	s_nop 0
	v_readlane_b32 s3, v16, 16
	v_readlane_b32 s5, v16, 48
	v_readlane_b32 s2, v16, 0
	v_readlane_b32 s4, v16, 32
	v_mov_b32_e32 v16, s3
	v_mov_b32_e32 v17, s5
	v_add_f32_e32 v16, s2, v16
	v_add_f32_e32 v17, s4, v17
	v_add_f32_e32 v16, v16, v17
	v_fmac_f32_e32 v56, 0xbc800000, v16
	v_mul_f32_e32 v16, v56, v56
	s_nop 1
	v_mov_b32_dpp v16, v16 quad_perm:[1,0,3,2] row_mask:0xf bank_mask:0xf bound_ctrl:1
	v_fmac_f32_e32 v16, v56, v56
	s_nop 1
	v_add_f32_dpp v16, v16, v16 quad_perm:[2,3,0,1] row_mask:0xf bank_mask:0xf bound_ctrl:1
	s_nop 1
	v_add_f32_dpp v16, v16, v16 row_half_mirror row_mask:0xf bank_mask:0xf bound_ctrl:1
	s_nop 1
	v_add_f32_dpp v16, v16, v16 row_mirror row_mask:0xf bank_mask:0xf bound_ctrl:1
	s_nop 0
	v_readlane_b32 s2, v16, 0
	v_readlane_b32 s4, v16, 16
	v_readlane_b32 s3, v16, 32
	v_readlane_b32 s5, v16, 48
	v_mov_b32_e32 v17, s4
	v_add_f32_e32 v17, s2, v17
	v_mov_b32_e32 v25, s5
	v_add_f32_e32 v25, s3, v25
	v_add_f32_e32 v17, v17, v25
	v_fmamk_f32 v17, v17, 0x3c800000, v210
	v_rsq_f32_e32 v17, v17
	s_nop 0
	v_mul_f32_e32 v56, v56, v17
	v_fmac_f32_e32 v59, v60, v56
	v_fmac_f32_e32 v59, v57, v61
	v_mul_f32_e32 v0, v58, v59
	v_bfe_u32 v24, v0, 16, 1
	v_add3_u32 v0, v0, v24, s85
	global_store_short_d16_hi v[14:15], v0, off
	s_waitcnt vmcnt(3)
	v_add_f32_dpp v16, v62, v62 quad_perm:[1,0,3,2] row_mask:0xf bank_mask:0xf bound_ctrl:1
	s_nop 1
	v_add_f32_dpp v16, v16, v16 quad_perm:[2,3,0,1] row_mask:0xf bank_mask:0xf bound_ctrl:1
	s_nop 1
	v_add_f32_dpp v16, v16, v16 row_half_mirror row_mask:0xf bank_mask:0xf bound_ctrl:1
	s_nop 1
	v_add_f32_dpp v16, v16, v16 row_mirror row_mask:0xf bank_mask:0xf bound_ctrl:1
	s_nop 0
	v_readlane_b32 s3, v16, 16
	v_readlane_b32 s5, v16, 48
	v_readlane_b32 s2, v16, 0
	v_readlane_b32 s4, v16, 32
	v_mov_b32_e32 v16, s3
	v_mov_b32_e32 v17, s5
	v_add_f32_e32 v16, s2, v16
	v_add_f32_e32 v17, s4, v17
	v_add_f32_e32 v16, v16, v17
	v_fmac_f32_e32 v62, 0xbc800000, v16
	v_mul_f32_e32 v16, v62, v62
	s_nop 1
	v_mov_b32_dpp v16, v16 quad_perm:[1,0,3,2] row_mask:0xf bank_mask:0xf bound_ctrl:1
	v_fmac_f32_e32 v16, v62, v62
	s_nop 1
	v_add_f32_dpp v16, v16, v16 quad_perm:[2,3,0,1] row_mask:0xf bank_mask:0xf bound_ctrl:1
	s_nop 1
	v_add_f32_dpp v16, v16, v16 row_half_mirror row_mask:0xf bank_mask:0xf bound_ctrl:1
	s_nop 1
	v_add_f32_dpp v16, v16, v16 row_mirror row_mask:0xf bank_mask:0xf bound_ctrl:1
	s_nop 0
	v_readlane_b32 s2, v16, 0
	v_readlane_b32 s4, v16, 16
	v_readlane_b32 s3, v16, 32
	v_readlane_b32 s5, v16, 48
	v_mov_b32_e32 v17, s4
	v_add_f32_e32 v17, s2, v17
	v_mov_b32_e32 v25, s5
	v_add_f32_e32 v25, s3, v25
	v_add_f32_e32 v17, v17, v25
	v_fmamk_f32 v17, v17, 0x3c800000, v210
	v_rsq_f32_e32 v17, v17
	s_nop 0
	v_mul_f32_e32 v62, v62, v17
	v_fmac_f32_e32 v65, v66, v62
	v_fmac_f32_e32 v65, v63, v67
	v_mul_f32_e32 v0, v64, v65
	v_bfe_u32 v24, v0, 16, 1
	v_add3_u32 v0, v0, v24, s85
	global_store_short_d16_hi v[14:15], v0, off offset:128
	s_add_i32 s27, s27, 4
	s_add_u32 s14, s14, 0x400
	s_addc_u32 s15, s15, 0
	s_add_u32 s12, s12, 0x3000
	s_addc_u32 s13, s13, 0
	s_add_u32 s16, s16, 16
	s_addc_u32 s17, s17, 0
	v_lshl_add_u64 v[14:15], v[14:15], 0, s[76:77]
	s_cmpk_eq_i32 s14, 0x1000
	s_cbranch_scc1 .LBB0_1737
	s_branch .LBB0_1740

.LBB0_2511:
	v_readlane_b32 s2, v253, 4
	v_mbcnt_lo_u32_b32 v12, -1, 0
	v_mbcnt_hi_u32_b32 v12, -1, v12
	v_readlane_b32 s3, v253, 8
	s_nop 0
	v_add_u32_e32 v0, s2, v12
	s_nop 0
	v_readfirstlane_b32 s2, v0
	s_ashr_i32 s2, s2, 6
	s_add_i32 s12, s2, s3
	s_cmpk_gt_i32 s12, 0x23ff
	s_cbranch_scc1 .LBB0_2514
	s_load_dwordx4 s[4:7], s[0:1], 0x1a0
	s_load_dwordx2 s[10:11], s[0:1], 0x1b0
	s_ashr_i32 s1, s2, 31
	s_add_u32 s0, s2, s3
	v_readlane_b32 s2, v253, 47
	s_addc_u32 s1, s1, s2
	s_lshl_b64 s[2:3], s[0:1], 2
	v_lshlrev_b32_e32 v0, 4, v12
	s_waitcnt lgkmcnt(0)
	s_add_u32 s2, s10, s2
	v_mov_b32_e32 v1, 0
	v_and_b32_e32 v0, 0x3f0, v0
	s_addc_u32 s3, s11, s3
	v_readlane_b32 s18, v253, 15
	v_lshl_add_u64 v[2:3], s[4:5], 0, v[0:1]
	v_or_b32_e32 v4, 0x1000, v0
	v_mov_b32_e32 v5, v1
	v_or_b32_e32 v6, 0x1400, v0
	v_mov_b32_e32 v7, v1
	v_or_b32_e32 v8, 0x1800, v0
	v_mov_b32_e32 v9, v1
	v_or_b32_e32 v0, 0x1c00, v0
	s_add_u32 s2, s2, 0x190000
	v_readlane_b32 s19, v253, 16
	v_lshl_add_u64 v[4:5], s[4:5], 0, v[4:5]
	v_lshl_add_u64 v[6:7], s[4:5], 0, v[6:7]
	v_lshl_add_u64 v[8:9], s[4:5], 0, v[8:9]
	v_lshl_add_u64 v[10:11], s[4:5], 0, v[0:1]
	s_addc_u32 s3, s3, 0
	s_lshl_b64 s[4:5], s[18:19], 2
	s_lshl_b64 s[0:1], s[0:1], 13
	s_add_u32 s6, s6, s0
	s_addc_u32 s7, s7, s1
	s_lshl_b64 s[8:9], s[18:19], 13
	v_and_b32_e32 v0, 63, v12
	s_add_u32 s10, s10, s0
	s_movk_i32 s13, 0x1000
	v_lshlrev_b32_e32 v0, 4, v0
	s_addc_u32 s11, s11, s1
	v_mov_b32_e32 v12, 0x358637bd
	s_mov_b32 s14, 0xf800000
	v_mov_b32_e32 v13, 0x260
	s_mov_b32 s15, 0x29200000
	s_mov_b32 s16, 0x29201000
	global_load_dwordx4 v[64:67], v[2:3], off
	global_load_dwordx4 v[68:71], v[2:3], off offset:1024
	global_load_dwordx4 v[72:75], v[2:3], off offset:2048
	global_load_dwordx4 v[76:79], v[2:3], off offset:3072
	global_load_dwordx4 v[80:83], v[4:5], off
	global_load_dwordx4 v[84:87], v[6:7], off
	global_load_dwordx4 v[88:91], v[8:9], off
	global_load_dwordx4 v[92:95], v[10:11], off
.LBB0_2513:
	global_load_dword v28, v1, s[2:3]
	v_lshl_add_u64 v[22:23], s[10:11], 0, v[0:1]
	v_add_co_u32_e32 v24, vcc, s16, v22
	v_lshl_add_u64 v[26:27], s[6:7], 0, v[0:1]
	s_nop 0
	v_addc_co_u32_e32 v25, vcc, 0, v23, vcc
	v_add_co_u32_e32 v22, vcc, s15, v22
	s_nop 1
	v_addc_co_u32_e32 v23, vcc, 0, v23, vcc
	v_add_co_u32_e32 v96, vcc, s13, v26
	s_nop 1
	v_addc_co_u32_e32 v97, vcc, 0, v27, vcc
	global_load_dwordx4 v[100:103], v[24:25], off offset:-4096
	global_load_dwordx4 v[104:107], v[22:23], off offset:1024
	global_load_dwordx4 v[108:111], v[22:23], off offset:2048
	global_load_dwordx4 v[112:115], v[22:23], off offset:3072
	global_load_dwordx4 v[116:119], v[24:25], off
	global_load_dwordx4 v[120:123], v[24:25], off offset:1024
	global_load_dwordx4 v[124:127], v[24:25], off offset:2048
	global_load_dwordx4 v[128:131], v[24:25], off offset:3072
	s_add_i32 s12, s12, s18
	s_add_u32 s2, s2, s4
	s_addc_u32 s3, s3, s5
	s_add_u32 s6, s6, s8
	s_addc_u32 s7, s7, s9
	s_add_u32 s10, s10, s8
	s_addc_u32 s11, s11, s9
	s_waitcnt vmcnt(8)
	v_fmamk_f32 v28, v28, 0x3a000000, v12
	v_mul_f32_e32 v29, 0x4f800000, v28
	v_cmp_gt_f32_e32 vcc, s14, v28
	s_nop 1
	v_cndmask_b32_e32 v28, v28, v29, vcc
	v_sqrt_f32_e32 v29, v28
	s_nop 0
	v_add_u32_e32 v30, -1, v29
	v_add_u32_e32 v31, 1, v29
	v_fma_f32 v32, -v30, v29, v28
	v_fma_f32 v33, -v31, v29, v28
	v_cmp_ge_f32_e64 s[0:1], 0, v32
	s_nop 1
	v_cndmask_b32_e64 v29, v29, v30, s[0:1]
	v_cmp_lt_f32_e64 s[0:1], 0, v33
	s_nop 1
	v_cndmask_b32_e64 v29, v29, v31, s[0:1]
	v_mul_f32_e32 v30, 0x37800000, v29
	v_cndmask_b32_e32 v29, v29, v30, vcc
	v_cmp_class_f32_e32 vcc, v28, v13
	s_nop 1
	v_cndmask_b32_e32 v28, v29, v28, vcc
	v_div_scale_f32 v29, s[0:1], v28, v28, 1.0
	v_rcp_f32_e32 v31, v29
	v_div_scale_f32 v30, vcc, 1.0, v28, 1.0
	v_fma_f32 v32, -v29, v31, 1.0
	v_fmac_f32_e32 v31, v32, v31
	v_mul_f32_e32 v32, v30, v31
	v_fma_f32 v33, -v29, v32, v30
	v_fmac_f32_e32 v32, v33, v31
	v_fma_f32 v29, -v29, v32, v30
	v_div_fmas_f32 v29, v29, v31, v32
	v_div_fixup_f32 v28, v29, v28, 1.0
	s_waitcnt vmcnt(7)
	v_pk_mul_f32 v[100:101], v[100:101], v[28:29] op_sel_hi:[1,0]
	v_pk_mul_f32 v[102:103], v[102:103], v[28:29] op_sel_hi:[1,0]
	v_pk_mul_f32 v[100:101], v[64:65], v[100:101]
	v_pk_mul_f32 v[102:103], v[66:67], v[102:103]
	global_store_dwordx4 v[26:27], v[100:103], off
	s_waitcnt vmcnt(7)
	v_pk_mul_f32 v[104:105], v[104:105], v[28:29] op_sel_hi:[1,0]
	v_pk_mul_f32 v[106:107], v[106:107], v[28:29] op_sel_hi:[1,0]
	v_pk_mul_f32 v[104:105], v[68:69], v[104:105]
	v_pk_mul_f32 v[106:107], v[70:71], v[106:107]
	global_store_dwordx4 v[26:27], v[104:107], off offset:1024
	s_waitcnt vmcnt(7)
	v_pk_mul_f32 v[108:109], v[108:109], v[28:29] op_sel_hi:[1,0]
	v_pk_mul_f32 v[110:111], v[110:111], v[28:29] op_sel_hi:[1,0]
	v_pk_mul_f32 v[108:109], v[72:73], v[108:109]
	v_pk_mul_f32 v[110:111], v[74:75], v[110:111]
	global_store_dwordx4 v[26:27], v[108:111], off offset:2048
	s_waitcnt vmcnt(7)
	v_pk_mul_f32 v[112:113], v[112:113], v[28:29] op_sel_hi:[1,0]
	v_pk_mul_f32 v[114:115], v[114:115], v[28:29] op_sel_hi:[1,0]
	v_pk_mul_f32 v[112:113], v[76:77], v[112:113]
	v_pk_mul_f32 v[114:115], v[78:79], v[114:115]
	global_store_dwordx4 v[26:27], v[112:115], off offset:3072
	s_waitcnt vmcnt(7)
	v_pk_mul_f32 v[116:117], v[116:117], v[28:29] op_sel_hi:[1,0]
	v_pk_mul_f32 v[118:119], v[118:119], v[28:29] op_sel_hi:[1,0]
	v_pk_mul_f32 v[116:117], v[80:81], v[116:117]
	v_pk_mul_f32 v[118:119], v[82:83], v[118:119]
	global_store_dwordx4 v[96:97], v[116:119], off
	s_waitcnt vmcnt(7)
	v_pk_mul_f32 v[120:121], v[120:121], v[28:29] op_sel_hi:[1,0]
	v_pk_mul_f32 v[122:123], v[122:123], v[28:29] op_sel_hi:[1,0]
	v_pk_mul_f32 v[120:121], v[84:85], v[120:121]
	v_pk_mul_f32 v[122:123], v[86:87], v[122:123]
	global_store_dwordx4 v[96:97], v[120:123], off offset:1024
	s_waitcnt vmcnt(7)
	v_pk_mul_f32 v[124:125], v[124:125], v[28:29] op_sel_hi:[1,0]
	v_pk_mul_f32 v[126:127], v[126:127], v[28:29] op_sel_hi:[1,0]
	v_pk_mul_f32 v[124:125], v[88:89], v[124:125]
	v_pk_mul_f32 v[126:127], v[90:91], v[126:127]
	global_store_dwordx4 v[96:97], v[124:127], off offset:2048
	s_waitcnt vmcnt(7)
	v_pk_mul_f32 v[128:129], v[128:129], v[28:29] op_sel_hi:[1,0]
	v_pk_mul_f32 v[130:131], v[130:131], v[28:29] op_sel_hi:[1,0]
	v_pk_mul_f32 v[128:129], v[92:93], v[128:129]
	v_pk_mul_f32 v[130:131], v[94:95], v[130:131]
	global_store_dwordx4 v[96:97], v[128:131], off offset:3072
	s_cmpk_lt_i32 s12, 0x2400
	s_cbranch_scc1 .LBB0_2513
